# attention loop: interleaved schedule plus half-tile stagger between waves 0-3 and 4-7 (conditional barrier sites), V tiles in a 6-deep ring using the unused half of each V image; same math
# speedup vs baseline: 1.0224x; 1.0076x over previous
; #define SBAR() __builtin_amdgcn_sched_barrier(0)
; #define SLOAD(i, k0) do { sr_[i].a0 = *reinterpret_cast<const bf16x8*>(&KVh[(size_t)((k0) + sr) * NKV + c16 * 8]); sr_[i].a1 = *reinterpret_cast<const bf16x8*>(&KVh[(size_t)((k0) + 32 + sr) * NKV + c16 * 8]); \
;     sr_[i].rr = *reinterpret_cast<const bf16x8*>(&KR[(size_t)((k0) + rkey) * 32 + rch * 8]); } while (0)
; #define SWRITE(b, i) do { if (isK) { *(bf16x8*)(K_lds + (b) * SHM_K + kst0) = sr_[i].a0; *(bf16x8*)(K_lds + (b) * SHM_K + kst1) = sr_[i].a1; } \
;     else { *(bf16x8*)(V_lds + (b) * SHM_V + vst0) = sr_[i].a0; *(bf16x8*)(V_lds + (b) * SHM_V + vst1) = sr_[i].a1; } \
;     if (rwr) *(bf16x8*)(K_lds + (b) * SHM_K + rst) = sr_[i].rr; } while (0)
; #define SWAIT() asm volatile("s_waitcnt vmcnt(3)" ::: "memory")
; __device__ __forceinline__ void attn_body(const bf16_t* __restrict__ Qb, const bf16_t* __restrict__ KVh, const bf16_t* __restrict__ KR, const float* __restrict__ ropeq,
;                                           bf16_t* __restrict__ Ob, int seq, char* lds, const int tid) {
;     ...
;     f32x16 pA0, pA1, pB0, pB1; float mnA, mnB, alA, alB; bf16x8 pa0, pa1, pa2, pa3; const int NT = seq / KVBLK;
;     constexpr int SE = 0, SO = 1;
;     SLOAD(SE, 0); asm volatile("s_waitcnt vmcnt(0)" ::: "memory"); SWRITE(0, SE); __syncthreads();
;     qkt(pA0, pA1, K_lds, qr, r32, hi); partialSM(pA0, pA1, m_reg, mnA, alA);
;     SLOAD(SO, KVBLK); if (2 < NT) SLOAD(SE, 2 * KVBLK);
;     SWAIT(); SWRITE(1, SO); __syncthreads();
;     int bp = 0, bc = 1, bn = 2;
;     for (int j = 1; j + 1 < NT; j += 2) {
;         SBAR(); qkt(pB0, pB1, K_lds + bc * SHM_K, qr, r32, hi);
;         finishSM(pA0, pA1, alA, l_reg, pa0, pa1, pa2, pa3); SBAR();
;         SLOAD(SO, (j + 2) * KVBLK); SBAR();
;         pv_d0(o, vb0 + bp * (int)SHM_V, pa0, pa1, pa2, pa3); partialSM(pB0, pB1, m_reg, mnB, alB);
;         SWAIT(); SWRITE(bn, SE);
.LBB0_51:
	s_or_b64 exec, exec, s[14:15]
	s_waitcnt vmcnt(3)
	v_max_f32_e32 v33, 0xf149f2ca, v44
	v_mov_b32_e32 v32, 0xf149f2ca
	v_cndmask_b32_e32 v179, v33, v32, vcc
	v_mul_f32_e32 v32, 0xbe16c740, v179
	v_pk_fma_f32 v[16:17], v[16:17], s[52:53], v[32:33] op_sel_hi:[1,0,0]
	s_lshr_b32 s14, s20, 4
	v_exp_f32_e32 v116, v16
	v_sub_f32_e32 v16, 0xf149f2ca, v33
	v_mul_f32_e32 v16, 0x3e16c740, v16
	v_exp_f32_e32 v16, v16
	v_pk_fma_f32 v[18:19], v[18:19], s[52:53], v[32:33] op_sel_hi:[1,0,0]
	v_pk_fma_f32 v[20:21], v[20:21], s[52:53], v[32:33] op_sel_hi:[1,0,0]
	v_pk_fma_f32 v[22:23], v[22:23], s[52:53], v[32:33] op_sel_hi:[1,0,0]
	v_pk_fma_f32 v[24:25], v[24:25], s[52:53], v[32:33] op_sel_hi:[1,0,0]
	v_pk_fma_f32 v[26:27], v[26:27], s[52:53], v[32:33] op_sel_hi:[1,0,0]
	v_pk_fma_f32 v[28:29], v[28:29], s[52:53], v[32:33] op_sel_hi:[1,0,0]
	v_pk_fma_f32 v[30:31], v[30:31], s[52:53], v[32:33] op_sel_hi:[1,0,0]
	s_and_b32 s14, s14, 15
	v_exp_f32_e32 v117, v17
	v_exp_f32_e32 v114, v18
	v_exp_f32_e32 v115, v19
	v_exp_f32_e32 v112, v20
	v_exp_f32_e32 v113, v21
	v_exp_f32_e32 v110, v22
	v_exp_f32_e32 v111, v23
	v_exp_f32_e32 v108, v24
	v_exp_f32_e32 v109, v25
	v_exp_f32_e32 v106, v26
	v_exp_f32_e32 v107, v27
	v_exp_f32_e32 v102, v28
	v_exp_f32_e32 v103, v29
	v_exp_f32_e32 v104, v30
	v_exp_f32_e32 v105, v31
	s_lshl_b32 s14, s14, 8
	v_pk_fma_f32 v[118:119], v[14:15], s[52:53], v[32:33] op_sel_hi:[1,0,0]
	s_add_u32 s6, s14, s6
	v_mov_b32_e32 v14, v65
	v_mov_b32_e32 v15, v65
	v_cndmask_b32_e64 v225, v16, 1.0, vcc
	v_pk_fma_f32 v[120:121], v[12:13], s[52:53], v[32:33] op_sel_hi:[1,0,0]
	v_pk_fma_f32 v[122:123], v[10:11], s[52:53], v[32:33] op_sel_hi:[1,0,0]
	v_pk_fma_f32 v[124:125], v[8:9], s[52:53], v[32:33] op_sel_hi:[1,0,0]
	v_pk_fma_f32 v[126:127], v[6:7], s[52:53], v[32:33] op_sel_hi:[1,0,0]
	v_pk_fma_f32 v[128:129], v[4:5], s[52:53], v[32:33] op_sel_hi:[1,0,0]
	v_pk_fma_f32 v[176:177], v[2:3], s[52:53], v[32:33] op_sel_hi:[1,0,0]
	v_pk_fma_f32 v[180:181], v[0:1], s[52:53], v[32:33] op_sel_hi:[1,0,0]
	s_addc_u32 s7, 0, s7
	v_mov_b32_e32 v0, v65
	v_mov_b32_e32 v1, v65
	v_mov_b32_e32 v2, v65
	v_mov_b32_e32 v3, v65
	v_mov_b32_e32 v4, v65
	v_mov_b32_e32 v5, v65
	v_mov_b32_e32 v6, v65
	v_mov_b32_e32 v7, v65
	v_mov_b32_e32 v8, v65
	v_mov_b32_e32 v9, v65
	v_mov_b32_e32 v10, v65
	v_mov_b32_e32 v11, v65
	v_mov_b32_e32 v12, v65
	v_mov_b32_e32 v13, v65
	v_mov_b64_e32 v[30:31], v[14:15]
	v_lshl_add_u64 v[168:169], s[6:7], 0, v[156:157]
	v_lshl_add_u64 v[170:171], v[158:159], 0, s[12:13]
	v_lshl_add_u64 v[172:173], v[160:161], 0, s[12:13]
	s_mov_b32 s16, 0
	v_mov_b32_e32 v163, 0
	s_mov_b32 s6, 2
	s_mov_b32 s17, 1
	v_mov_b64_e32 v[28:29], v[12:13]
	v_mov_b64_e32 v[26:27], v[10:11]
	v_mov_b64_e32 v[24:25], v[8:9]
	v_mov_b64_e32 v[22:23], v[6:7]
	v_mov_b64_e32 v[20:21], v[4:5]
	v_mov_b64_e32 v[18:19], v[2:3]
	v_mov_b64_e32 v[16:17], v[0:1]
	s_mov_b32 s18, 1
	s_load_dwordx2 s[26:27], s[94:95], 0xb8
	s_mov_b32 s24, 0x2000
	s_mov_b32 s25, 0
	s_mov_b32 s58, 0
	s_mov_b32 s59, 0
	s_mov_b32 s60, 0x400
	s_waitcnt lgkmcnt(0)
	s_add_u32 s28, s26, 0x10cc0000
	s_addc_u32 s29, s27, 0
	s_add_u32 s30, s26, 0x10ce0000
	s_addc_u32 s31, s27, 0
	s_add_u32 s40, s26, 0x10d00000
	s_addc_u32 s41, s27, 0
	s_add_u32 s42, s26, 0x10d20000
	s_addc_u32 s43, s27, 0
	s_waitcnt lgkmcnt(0)
	s_barrier
.Lattn_loop:
	s_mov_b32 s19, s6
	s_lshl_b32 s14, s18, 14
	s_lshl_b32 s22, s16, 14
	s_lshl_b32 s15, s19, 14
	s_add_u32 s61, s22, s58
	v_add_u32_e32 v254, s14, v188
	ds_read_b128 v[234:237], v254 offset:49152
	ds_read_b128 v[238:241], v254 offset:57344
	v_add_u32_e32 v254, s14, v189
	ds_read_b128 v[242:245], v254 offset:49152
	ds_read_b128 v[246:249], v254 offset:57344
	v_exp_f32_e32 v226, v124
	v_exp_f32_e32 v227, v125
	v_add_f32_e32 v250, v116, v114
	v_add_f32_e32 v251, v117, v115
	v_add_f32_e32 v250, v112, v250
	v_add_f32_e32 v251, v113, v251
	v_exp_f32_e32 v228, v122
	v_exp_f32_e32 v229, v123
	s_waitcnt lgkmcnt(3)
	v_mfma_f32_32x32x16_bf16 v[48:63], v[234:237], v[78:81], 0
	v_add_f32_e32 v250, v110, v250
	v_add_f32_e32 v251, v111, v251
	v_add_f32_e32 v250, v108, v250
	v_add_f32_e32 v251, v109, v251
	v_exp_f32_e32 v230, v120
	v_exp_f32_e32 v231, v121
	v_add_f32_e32 v250, v106, v250
	v_add_f32_e32 v251, v107, v251
	s_waitcnt lgkmcnt(2)
	v_mfma_f32_32x32x16_bf16 v[32:47], v[238:241], v[78:81], 0
	v_add_u32_e32 v254, s14, v212
	ds_read_b128 v[234:237], v254 offset:49152
	ds_read_b128 v[238:241], v254 offset:57344
	v_add_f32_e32 v250, v102, v250
	v_add_f32_e32 v251, v103, v251
	v_exp_f32_e32 v232, v118
	v_exp_f32_e32 v233, v119
	v_add_f32_e32 v250, v104, v250
	v_add_f32_e32 v251, v105, v251
	v_cvt_pk_bf16_f32 v116, v116, v117
	s_waitcnt lgkmcnt(3)
	v_mfma_f32_32x32x16_bf16 v[48:63], v[242:245], v[74:77], v[48:63]
	v_cvt_pk_bf16_f32 v117, v114, v115
	v_cvt_pk_bf16_f32 v118, v112, v113
	v_cvt_pk_bf16_f32 v119, v110, v111
	s_nop 0
	v_permlane32_swap_b32_e32 v116, v118
	v_permlane32_swap_b32_e32 v117, v119
	s_waitcnt lgkmcnt(2)
	v_mfma_f32_32x32x16_bf16 v[32:47], v[246:249], v[74:77], v[32:47]
	v_add_u32_e32 v254, s14, v213
	ds_read_b128 v[242:245], v254 offset:49152
	ds_read_b128 v[246:249], v254 offset:57344
	v_cvt_pk_bf16_f32 v120, v108, v109
	v_cvt_pk_bf16_f32 v121, v106, v107
	v_cvt_pk_bf16_f32 v122, v102, v103
	v_cvt_pk_bf16_f32 v123, v104, v105
	s_nop 0
	v_permlane32_swap_b32_e32 v120, v122
	s_waitcnt lgkmcnt(3)
	v_mfma_f32_32x32x16_bf16 v[48:63], v[234:237], v[70:73], v[48:63]
	v_permlane32_swap_b32_e32 v121, v123
	v_exp_f32_e32 v180, v180
	v_exp_f32_e32 v181, v181
	v_exp_f32_e32 v176, v176
	v_exp_f32_e32 v177, v177
	s_waitcnt vmcnt(0)
	s_xor_b32 s60, s60, 0x400
	v_mov_b32_e32 v255, s60
	v_cndmask_b32_e64 v255, 0, v255, s[0:1]
	v_add3_u32 v254, s15, v217, v255
	v_add_u32_e32 v255, v254, v218
	v_add_u32_e32 v254, v254, v219
	ds_write_b128 v255, v[90:93]
	ds_write_b128 v254, v[94:97]
	s_cmp_eq_u64 s[2:3], 0
	s_cbranch_scc1 .Lattn_swB
	v_add_u32_e32 v254, s15, v186
	ds_write_b128 v254, v[98:101] offset:49152
; #define SBAR() __builtin_amdgcn_sched_barrier(0)
; __device__ __forceinline__ void partialSM(f32x16& p0, f32x16& p1, float& m_reg, float& mn, float& alpha) {
;     constexpr float Cc = SCALE * 1.4426950408889634f;
;     float pmax = p0[0];
; #pragma unroll
;     for (int r = 1; r < 16; ++r) pmax = fmaxf(pmax, p0[r]);
; #pragma unroll
;     for (int r = 0; r < 16; ++r) pmax = fmaxf(pmax, p1[r]);
; __device__ __forceinline__ void qkt(f32x16& p0, f32x16& p1, const char* Ks, const bf16x8* qr, int r32, int hi) {
;     p0 = f32x16{}; p1 = f32x16{};
; #pragma unroll
;     for (int d0 = 0; d0 < 6; ++d0) { const int cb = (d0 * 16 + hi * 8) * 2;
;         bf16x8 b0 = *reinterpret_cast<const bf16x8*>(Ks + KSWZ(r32, cb));
;         bf16x8 b1 = *reinterpret_cast<const bf16x8*>(Ks + KSWZ(32 + r32, cb));
;         p0 = __builtin_amdgcn_mfma_f32_32x32x16_bf16(b0, qr[d0], p0, 0, 0, 0);
;         p1 = __builtin_amdgcn_mfma_f32_32x32x16_bf16(b1, qr[d0], p1, 0, 0, 0); }
; }
; __device__ __forceinline__ int v_st(int k, int c) { const int kk = (k & ~0xC) | ((k & 4) << 1) | ((k & 8) >> 1); return ((kk >> 3) * 4 + (c >> 5)) * 512 + ((kk & 7) * 32 + (c & 31)) * 2; }
; __device__ __forceinline__ int v_rd_base(int lane) { return ((lane & 3) << 3) | (((lane >> 2) & 3) << 6) | (((lane >> 4) & 1) << 5) | (((lane >> 5) & 1) << 8); }
; template <int OFF> __device__ __forceinline__ s16x4 tr_read(int vb) {
;     s16x4 r; asm volatile("ds_read_b64_tr_b16 %0, %1 offset:%2" : "=&v"(r) : "v"(vb), "i"(OFF) : "memory"); return r;
; }
; template <int D0> __device__ __forceinline__ void pv_one(f32x16& od, int vb, bf16x8 pa0, bf16x8 pa1, bf16x8 pa2, bf16x8 pa3) {
;     const s16x4 l0 = tr_read<v_rd_off(D0, 0, 0)>(vb), h0 = tr_read<v_rd_off(D0, 0, 1)>(vb), l1 = tr_read<v_rd_off(D0, 1, 0)>(vb), h1 = tr_read<v_rd_off(D0, 1, 1)>(vb);
;     const s16x4 l2 = tr_read<v_rd_off(D0, 2, 0)>(vb), h2 = tr_read<v_rd_off(D0, 2, 1)>(vb), l3 = tr_read<v_rd_off(D0, 3, 0)>(vb), h3 = tr_read<v_rd_off(D0, 3, 1)>(vb);
;     asm volatile("s_waitcnt lgkmcnt(0)" ::: "memory"); SBAR();
;     ...
;     od = __builtin_amdgcn_mfma_f32_32x32x16_bf16(pa0, PK(l0, h0), od, 0, 0, 0);
;     od = __builtin_amdgcn_mfma_f32_32x32x16_bf16(pa1, PK(l1, h1), od, 0, 0, 0);
;     od = __builtin_amdgcn_mfma_f32_32x32x16_bf16(pa2, PK(l2, h2), od, 0, 0, 0);
;     od = __builtin_amdgcn_mfma_f32_32x32x16_bf16(pa3, PK(l3, h3), od, 0, 0, 0);
;     ...
; }
.Lattn_swB:
	s_waitcnt lgkmcnt(4)
	v_mfma_f32_32x32x16_bf16 v[32:47], v[238:241], v[70:73], v[32:47]
	v_add_u32_e32 v254, s14, v214
	ds_read_b128 v[234:237], v254 offset:49152
	ds_read_b128 v[238:241], v254 offset:57344
	v_exp_f32_e32 v128, v128
	v_exp_f32_e32 v129, v129
	v_exp_f32_e32 v202, v126
	v_exp_f32_e32 v203, v127
	s_waitcnt lgkmcnt(5)
	v_mfma_f32_32x32x16_bf16 v[48:63], v[242:245], v[66:69], v[48:63]
	v_add_f32_e32 v174, v180, v176
	v_add_f32_e32 v175, v181, v177
	v_add_f32_e32 v174, v128, v174
	v_add_f32_e32 v175, v129, v175
	v_add_f32_e32 v174, v202, v174
	v_add_f32_e32 v175, v203, v175
	v_add_f32_e32 v174, v226, v174
	v_add_f32_e32 v175, v227, v175
	v_lshl_add_u64 v[106:107], s[28:29], 0, v[168:169]
	global_load_dwordx4 v[106:109], v[106:107], off
	v_lshl_add_u64 v[110:111], s[30:31], 0, v[168:169]
	global_load_dwordx4 v[110:113], v[110:111], off
	v_lshl_add_u64 v[102:103], s[26:27], 0, v[172:173]
	global_load_dwordx4 v[102:105], v[102:103], off
	s_waitcnt lgkmcnt(4)
	v_mfma_f32_32x32x16_bf16 v[32:47], v[246:249], v[66:69], v[32:47]
	v_add_u32_e32 v254, s14, v215
	ds_read_b128 v[242:245], v254 offset:49152
	ds_read_b128 v[246:249], v254 offset:57344
	v_add_f32_e32 v174, v228, v174
	v_add_f32_e32 v175, v229, v175
	v_add_f32_e32 v174, v230, v174
	v_add_f32_e32 v175, v231, v175
	v_add_f32_e32 v174, v232, v174
	v_add_f32_e32 v175, v233, v175
	v_add_f32_e32 v250, v250, v174
	v_add_f32_e32 v251, v251, v175
	s_waitcnt lgkmcnt(3)
	v_mfma_f32_32x32x16_bf16 v[48:63], v[234:237], v[82:85], v[48:63]
	v_add_f32_e32 v174, v250, v251
	v_add_f32_e32 v175, v251, v250
	v_mov_b32_e32 v175, v174
	s_nop 1
	v_permlane32_swap_b32_e32 v174, v175
	v_cvt_pk_bf16_f32 v124, v180, v181
	s_waitcnt lgkmcnt(2)
	v_mfma_f32_32x32x16_bf16 v[32:47], v[238:241], v[82:85], v[32:47]
	v_add_u32_e32 v255, s61, v185
	ds_read_b64_tr_b16 v[234:235], v255 offset:0
	ds_read_b64_tr_b16 v[236:237], v255 offset:2048
	ds_read_b64_tr_b16 v[238:239], v255 offset:4096
	ds_read_b64_tr_b16 v[240:241], v255 offset:6144
	v_cvt_pk_bf16_f32 v125, v176, v177
	v_cvt_pk_bf16_f32 v126, v128, v129
	v_cvt_pk_bf16_f32 v127, v202, v203
	s_nop 0
	v_permlane32_swap_b32_e32 v124, v126
	s_waitcnt lgkmcnt(5)
	v_mfma_f32_32x32x16_bf16 v[48:63], v[242:245], v[86:89], v[48:63]
	v_permlane32_swap_b32_e32 v125, v127
	v_cvt_pk_bf16_f32 v226, v226, v227
	v_cvt_pk_bf16_f32 v227, v228, v229
	v_cvt_pk_bf16_f32 v228, v230, v231
	s_waitcnt lgkmcnt(4)
	v_mfma_f32_32x32x16_bf16 v[32:47], v[246:249], v[86:89], v[32:47]
	ds_read_b64_tr_b16 v[242:243], v255 offset:8192
	ds_read_b64_tr_b16 v[244:245], v255 offset:10240
	ds_read_b64_tr_b16 v[246:247], v255 offset:12288
	ds_read_b64_tr_b16 v[248:249], v255 offset:14336
	v_cvt_pk_bf16_f32 v229, v232, v233
	v_permlane32_swap_b32_e32 v226, v228
	s_nop 0
	v_permlane32_swap_b32_e32 v227, v229
	s_waitcnt lgkmcnt(8)
	s_cmp_eq_u64 s[2:3], 0
	s_cbranch_scc0 .Lattn_cb1
	s_barrier
.Lattn_cb1:
	s_waitcnt lgkmcnt(6)
	v_mfma_f32_32x32x16_bf16 v[0:15], v[116:119], v[234:237], v[0:15]
	ds_read_b64_tr_b16 v[234:235], v255 offset:512
	ds_read_b64_tr_b16 v[236:237], v255 offset:2560
	v_max_f32_e32 v90, v48, v49
	v_max_f32_e32 v91, v32, v33
	v_max3_f32 v90, v90, v50, v51
	v_max3_f32 v91, v91, v34, v35
	v_max3_f32 v90, v90, v52, v53
	v_max3_f32 v91, v91, v36, v37
	s_waitcnt lgkmcnt(6)
	v_mfma_f32_32x32x16_bf16 v[0:15], v[120:123], v[238:241], v[0:15]
	ds_read_b64_tr_b16 v[238:239], v255 offset:4608
	ds_read_b64_tr_b16 v[240:241], v255 offset:6656
	v_max3_f32 v90, v90, v54, v55
	v_max3_f32 v91, v91, v38, v39
	v_max3_f32 v90, v90, v56, v57
	v_max3_f32 v91, v91, v40, v41
	v_max3_f32 v90, v90, v58, v59
	v_max3_f32 v91, v91, v42, v43
	v_max3_f32 v90, v90, v60, v61
	s_waitcnt lgkmcnt(6)
	v_mfma_f32_32x32x16_bf16 v[0:15], v[124:127], v[242:245], v[0:15]
	ds_read_b64_tr_b16 v[242:243], v255 offset:8704
	ds_read_b64_tr_b16 v[244:245], v255 offset:10752
	v_max3_f32 v91, v91, v44, v45
	v_max3_f32 v90, v90, v62, v63
	v_max3_f32 v91, v91, v46, v47
	v_max_f32_e32 v90, v90, v91
	v_mov_b32_e32 v91, v90
	s_nop 1
	v_permlane32_swap_b32_e32 v90, v91
	v_max_f32_e32 v90, v90, v91
	s_waitcnt lgkmcnt(6)
	v_mfma_f32_32x32x16_bf16 v[0:15], v[226:229], v[246:249], v[0:15]
	ds_read_b64_tr_b16 v[246:247], v255 offset:12800
	ds_read_b64_tr_b16 v[248:249], v255 offset:14848
	v_sub_f32_e32 v92, v90, v179
	v_cmp_ge_f32_e32 vcc, s67, v92
	v_max_f32_e32 v90, v179, v90
	v_sub_f32_e32 v92, v179, v90
	v_mul_f32_e32 v92, 0x3e16c740, v92
	v_exp_f32_e32 v93, v92
	s_cmp_eq_u64 vcc, exec
	s_waitcnt lgkmcnt(6)
	v_mfma_f32_32x32x16_bf16 v[16:31], v[116:119], v[234:237], v[16:31]
	s_cselect_b64 s[44:45], -1, 0
	v_cndmask_b32_e64 v180, v90, v179, s[44:45]
	v_mul_f32_e32 v94, 0xbe16c740, v180
	v_fma_f32 v48, v48, s52, v94
	v_fma_f32 v49, v49, s52, v94
	v_fma_f32 v50, v50, s52, v94
	v_fma_f32 v51, v51, s52, v94
	v_fma_f32 v52, v52, s52, v94
	v_fma_f32 v53, v53, s52, v94
	v_exp_f32_e32 v234, v50
	v_exp_f32_e32 v235, v51
	v_exp_f32_e32 v236, v52
	v_exp_f32_e32 v237, v53
	s_waitcnt lgkmcnt(4)
	v_mfma_f32_32x32x16_bf16 v[16:31], v[120:123], v[238:241], v[16:31]
	v_fma_f32 v54, v54, s52, v94
	v_fma_f32 v55, v55, s52, v94
	v_fma_f32 v56, v56, s52, v94
	v_fma_f32 v57, v57, s52, v94
	v_fma_f32 v58, v58, s52, v94
	v_fma_f32 v59, v59, s52, v94
	v_fma_f32 v60, v60, s52, v94
	v_fma_f32 v61, v61, s52, v94
	v_fma_f32 v62, v62, s52, v94
	v_fma_f32 v63, v63, s52, v94
	v_fma_f32 v128, v38, s52, v94
	v_fma_f32 v129, v39, s52, v94
	v_exp_f32_e32 v238, v54
	v_exp_f32_e32 v239, v55
	v_exp_f32_e32 v240, v56
	v_exp_f32_e32 v241, v57
	v_fma_f32 v122, v32, s52, v94
	v_fma_f32 v123, v33, s52, v94
	s_waitcnt lgkmcnt(2)
	v_mfma_f32_32x32x16_bf16 v[16:31], v[124:127], v[242:245], v[16:31]
	v_fma_f32 v178, v40, s52, v94
	v_fma_f32 v179, v41, s52, v94
	v_fma_f32 v202, v42, s52, v94
	v_fma_f32 v203, v43, s52, v94
	v_fma_f32 v230, v46, s52, v94
	v_fma_f32 v231, v47, s52, v94
	v_exp_f32_e32 v232, v48
	v_exp_f32_e32 v233, v49
	v_exp_f32_e32 v242, v58
	v_exp_f32_e32 v243, v59
	v_exp_f32_e32 v244, v60
	v_exp_f32_e32 v245, v61
	v_fma_f32 v124, v34, s52, v94
	v_fma_f32 v125, v35, s52, v94
	v_fma_f32 v126, v36, s52, v94
	v_fma_f32 v127, v37, s52, v94
	s_waitcnt lgkmcnt(0)
	v_mfma_f32_32x32x16_bf16 v[16:31], v[226:229], v[246:249], v[16:31]
	v_exp_f32_e32 v246, v62
	v_exp_f32_e32 v247, v63
	v_fma_f32 v228, v44, s52, v94
	v_fma_f32 v229, v45, s52, v94
	v_cndmask_b32_e64 v227, v93, 1.0, s[44:45]
	v_cmp_gt_f32_e32 vcc, 1.0, v227
	s_cbranch_vccz .Lattn_rsB
; #define SBAR() __builtin_amdgcn_sched_barrier(0)
; #define SLOAD(i, k0) do { sr_[i].a0 = *reinterpret_cast<const bf16x8*>(&KVh[(size_t)((k0) + sr) * NKV + c16 * 8]); sr_[i].a1 = *reinterpret_cast<const bf16x8*>(&KVh[(size_t)((k0) + 32 + sr) * NKV + c16 * 8]); \
;     sr_[i].rr = *reinterpret_cast<const bf16x8*>(&KR[(size_t)((k0) + rkey) * 32 + rch * 8]); } while (0)
; #define SWRITE(b, i) do { if (isK) { *(bf16x8*)(K_lds + (b) * SHM_K + kst0) = sr_[i].a0; *(bf16x8*)(K_lds + (b) * SHM_K + kst1) = sr_[i].a1; } \
;     else { *(bf16x8*)(V_lds + (b) * SHM_V + vst0) = sr_[i].a0; *(bf16x8*)(V_lds + (b) * SHM_V + vst1) = sr_[i].a1; } \
;     if (rwr) *(bf16x8*)(K_lds + (b) * SHM_K + rst) = sr_[i].rr; } while (0)
; #define SWAIT() asm volatile("s_waitcnt vmcnt(3)" ::: "memory")
; __device__ __forceinline__ void finishSM(f32x16& p0, f32x16& p1, float alpha, float& l_reg, bf16x8& pa0, bf16x8& pa1, bf16x8& pa2, bf16x8& pa3) {
; #pragma unroll
;     for (int r = 0; r < 16; ++r) p1[r] = __builtin_amdgcn_exp2f(p1[r]);
;     float ps;
;     { typedef float f32x2 __attribute__((ext_vector_type(2))); f32x2 s0 = {p0[0], p0[1]}, s1 = {p1[0], p1[1]};
; #pragma unroll
;       for (int r = 2; r < 16; r += 2) { s0 += (f32x2){p0[r], p0[r + 1]}; s1 += (f32x2){p1[r], p1[r + 1]}; }
;       s0 += s1; ps = s0.x + s0.y; }
;     { auto rr = __builtin_amdgcn_permlane32_swap(__float_as_uint(ps), __float_as_uint(ps), false, false);
;       ps = __uint_as_float(rr[0]) + __uint_as_float(rr[1]); }
;     l_reg = l_reg * alpha + ps;
;     ...
;     PK4(p0, 0, pa0); PK4(p0, 8, pa1); PK4(p1, 0, pa2); PK4(p1, 8, pa3);
; __device__ __forceinline__ void attn_body(const bf16_t* __restrict__ Qb, const bf16_t* __restrict__ KVh, const bf16_t* __restrict__ KR, const float* __restrict__ ropeq,
;                                           bf16_t* __restrict__ Ob, int seq, char* lds, const int tid) {
;     ...
;         RESC(alB); __syncthreads();
;         { const int t = bp; bp = bc; bc = bn; bn = t; }
;         SBAR(); qkt(pA0, pA1, K_lds + bc * SHM_K, qr, r32, hi);
;         finishSM(pB0, pB1, alB, l_reg, pa0, pa1, pa2, pa3); SBAR();
;         if (j + 3 < NT) SLOAD(SE, (j + 3) * KVBLK); SBAR();
;         pv_d0(o, vb0 + bp * (int)SHM_V, pa0, pa1, pa2, pa3); partialSM(pA0, pA1, m_reg, mnA, alA);
;         SWAIT(); SWRITE(bn, SO);
	s_nop 7
	s_nop 5
	s_and_saveexec_b64 s[46:47], s[4:5]
	ds_write_b32 v216, v227 offset:128
	s_or_b64 exec, exec, s[46:47]
	s_waitcnt lgkmcnt(0)
	v_add_u32_e32 v96, v139, v187
	ds_read_b128 v[116:119], v96 offset:192
	ds_read_b128 v[92:95], v96 offset:160
	ds_read_b128 v[248:251], v96 offset:128
	ds_read_b128 v[96:99], v96 offset:224
	s_waitcnt lgkmcnt(0)
	v_mul_f32_e32 v12, v12, v96
	v_mul_f32_e32 v13, v13, v97
	v_mul_f32_e32 v14, v14, v98
	v_mul_f32_e32 v15, v15, v99
	v_mul_f32_e32 v8, v8, v116
	v_mul_f32_e32 v9, v9, v117
	v_mul_f32_e32 v10, v10, v118
	v_mul_f32_e32 v11, v11, v119
	v_mul_f32_e32 v4, v4, v92
	v_mul_f32_e32 v5, v5, v93
	v_mul_f32_e32 v6, v6, v94
	v_mul_f32_e32 v7, v7, v95
	v_mul_f32_e32 v0, v0, v248
	v_mul_f32_e32 v1, v1, v249
	v_mul_f32_e32 v2, v2, v250
	v_mul_f32_e32 v3, v3, v251
	v_mul_f32_e32 v28, v28, v96
	v_mul_f32_e32 v29, v29, v97
	v_mul_f32_e32 v30, v30, v98
	v_mul_f32_e32 v31, v31, v99
	v_mul_f32_e32 v24, v24, v116
	v_mul_f32_e32 v25, v25, v117
	v_mul_f32_e32 v26, v26, v118
	v_mul_f32_e32 v27, v27, v119
	v_mul_f32_e32 v20, v20, v92
	v_mul_f32_e32 v21, v21, v93
	v_mul_f32_e32 v22, v22, v94
	v_mul_f32_e32 v23, v23, v95
	v_mul_f32_e32 v16, v16, v248
	v_mul_f32_e32 v17, v17, v249
	v_mul_f32_e32 v18, v18, v250
	v_mul_f32_e32 v19, v19, v251
.Lattn_rsB:
	s_waitcnt lgkmcnt(0)
	s_cmp_eq_u64 s[2:3], 0
	s_cbranch_scc1 .Lattn_cb2
	s_barrier
.Lattn_cb2:
	s_add_u32 s63, s14, s59
	v_add_u32_e32 v254, s15, v188
	ds_read_b128 v[114:117], v254 offset:49152
	ds_read_b128 v[118:121], v254 offset:57344
	v_add_f32_e32 v176, v232, v234
	v_add_f32_e32 v177, v233, v235
	v_cvt_pk_bf16_f32 v232, v232, v233
	v_cvt_pk_bf16_f32 v233, v234, v235
	v_add_f32_e32 v176, v236, v176
	v_add_f32_e32 v177, v237, v177
	v_cvt_pk_bf16_f32 v234, v236, v237
	v_add_f32_e32 v176, v238, v176
	v_add_f32_e32 v177, v239, v177
	v_cvt_pk_bf16_f32 v235, v238, v239
	v_add_f32_e32 v176, v240, v176
	v_add_f32_e32 v177, v241, v177
	v_cvt_pk_bf16_f32 v236, v240, v241
	v_add_f32_e32 v176, v242, v176
	v_add_f32_e32 v177, v243, v177
	v_cvt_pk_bf16_f32 v237, v242, v243
	v_add_u32_e32 v254, s15, v189
	ds_read_b128 v[248:251], v254 offset:49152
	ds_read_b128 v[240:243], v254 offset:57344
	v_add_f32_e32 v176, v244, v176
	v_add_f32_e32 v177, v245, v177
	v_cvt_pk_bf16_f32 v238, v244, v245
	s_waitcnt lgkmcnt(3)
	v_mfma_f32_32x32x16_bf16 v[48:63], v[114:117], v[78:81], 0
	v_add_f32_e32 v176, v246, v176
	v_add_f32_e32 v177, v247, v177
	v_cvt_pk_bf16_f32 v239, v246, v247
	v_permlane32_swap_b32_e32 v232, v234
	v_permlane32_swap_b32_e32 v233, v235
	s_waitcnt lgkmcnt(2)
	v_mfma_f32_32x32x16_bf16 v[32:47], v[118:121], v[78:81], 0
	v_add_u32_e32 v254, s15, v212
	ds_read_b128 v[114:117], v254 offset:49152
	ds_read_b128 v[118:121], v254 offset:57344
	v_permlane32_swap_b32_e32 v236, v238
	v_permlane32_swap_b32_e32 v237, v239
	v_exp_f32_e32 v122, v122
	v_exp_f32_e32 v123, v123
	s_waitcnt lgkmcnt(3)
	v_mfma_f32_32x32x16_bf16 v[48:63], v[248:251], v[74:77], v[48:63]
	v_exp_f32_e32 v124, v124
	v_exp_f32_e32 v125, v125
	v_exp_f32_e32 v126, v126
	v_exp_f32_e32 v127, v127
	v_add_f32_e32 v244, v122, v124
	v_add_f32_e32 v245, v123, v125
	s_waitcnt lgkmcnt(2)
	v_mfma_f32_32x32x16_bf16 v[32:47], v[240:243], v[74:77], v[32:47]
	v_add_u32_e32 v254, s15, v213
	ds_read_b128 v[248:251], v254 offset:49152
	ds_read_b128 v[240:243], v254 offset:57344
	v_exp_f32_e32 v128, v128
	v_exp_f32_e32 v129, v129
	v_add_f32_e32 v244, v126, v244
	v_add_f32_e32 v245, v127, v245
	v_exp_f32_e32 v178, v178
	v_exp_f32_e32 v179, v179
	s_waitcnt lgkmcnt(3)
	v_mfma_f32_32x32x16_bf16 v[48:63], v[114:117], v[70:73], v[48:63]
	v_add_f32_e32 v244, v128, v244
	v_add_f32_e32 v245, v129, v245
	v_exp_f32_e32 v202, v202
	v_exp_f32_e32 v203, v203
	v_add_f32_e32 v244, v178, v244
	v_add_f32_e32 v245, v179, v245
	v_exp_f32_e32 v228, v228
	s_waitcnt vmcnt(0)
	s_xor_b32 s58, s58, 0x400
	v_mov_b32_e32 v255, s58
	v_cndmask_b32_e64 v255, 0, v255, s[0:1]
	v_add3_u32 v254, s22, v217, v255
	v_add_u32_e32 v255, v254, v218
	v_add_u32_e32 v254, v254, v219
	ds_write_b128 v255, v[106:109]
	ds_write_b128 v254, v[110:113]
	s_cmp_eq_u64 s[2:3], 0
	s_cbranch_scc1 .Lattn_swA
	v_add_u32_e32 v254, s22, v186
	ds_write_b128 v254, v[102:105] offset:49152

; #define SBAR() __builtin_amdgcn_sched_barrier(0)
; #define SLOAD(i, k0) do { sr_[i].a0 = *reinterpret_cast<const bf16x8*>(&KVh[(size_t)((k0) + sr) * NKV + c16 * 8]); sr_[i].a1 = *reinterpret_cast<const bf16x8*>(&KVh[(size_t)((k0) + 32 + sr) * NKV + c16 * 8]); \
;     sr_[i].rr = *reinterpret_cast<const bf16x8*>(&KR[(size_t)((k0) + rkey) * 32 + rch * 8]); } while (0)
; template <int D0> __device__ __forceinline__ void pv_one(f32x16& od, int vb, bf16x8 pa0, bf16x8 pa1, bf16x8 pa2, bf16x8 pa3) {
;     const s16x4 l0 = tr_read<v_rd_off(D0, 0, 0)>(vb), h0 = tr_read<v_rd_off(D0, 0, 1)>(vb), l1 = tr_read<v_rd_off(D0, 1, 0)>(vb), h1 = tr_read<v_rd_off(D0, 1, 1)>(vb);
;     const s16x4 l2 = tr_read<v_rd_off(D0, 2, 0)>(vb), h2 = tr_read<v_rd_off(D0, 2, 1)>(vb), l3 = tr_read<v_rd_off(D0, 3, 0)>(vb), h3 = tr_read<v_rd_off(D0, 3, 1)>(vb);
;     asm volatile("s_waitcnt lgkmcnt(0)" ::: "memory"); SBAR();
;     ...
;     od = __builtin_amdgcn_mfma_f32_32x32x16_bf16(pa0, PK(l0, h0), od, 0, 0, 0);
;     od = __builtin_amdgcn_mfma_f32_32x32x16_bf16(pa1, PK(l1, h1), od, 0, 0, 0);
;     od = __builtin_amdgcn_mfma_f32_32x32x16_bf16(pa2, PK(l2, h2), od, 0, 0, 0);
;     od = __builtin_amdgcn_mfma_f32_32x32x16_bf16(pa3, PK(l3, h3), od, 0, 0, 0);
;     ...
; }
; __device__ __forceinline__ void attn_body(const bf16_t* __restrict__ Qb, const bf16_t* __restrict__ KVh, const bf16_t* __restrict__ KR, const float* __restrict__ ropeq,
;                                           bf16_t* __restrict__ Ob, int seq, char* lds, const int tid) {
;     ...
;         SBAR(); qkt(pA0, pA1, K_lds + bc * SHM_K, qr, r32, hi);
;         finishSM(pB0, pB1, alB, l_reg, pa0, pa1, pa2, pa3); SBAR();
;         if (j + 3 < NT) SLOAD(SE, (j + 3) * KVBLK); SBAR();
;         pv_d0(o, vb0 + bp * (int)SHM_V, pa0, pa1, pa2, pa3); partialSM(pA0, pA1, m_reg, mnA, alA);
.Lattn_slA:
	s_waitcnt lgkmcnt(5)
	v_mfma_f32_32x32x16_bf16 v[48:63], v[248:251], v[66:69], v[48:63]
	v_add_f32_e32 v244, v230, v244
	v_add_f32_e32 v245, v231, v245
	v_add_f32_e32 v176, v244, v176
	v_add_f32_e32 v177, v245, v177
	v_cvt_pk_bf16_f32 v122, v122, v123
	v_cvt_pk_bf16_f32 v123, v124, v125
	v_cvt_pk_bf16_f32 v124, v126, v127
	s_waitcnt lgkmcnt(4)
	v_mfma_f32_32x32x16_bf16 v[32:47], v[240:243], v[66:69], v[32:47]
	v_add_u32_e32 v254, s15, v215
	ds_read_b128 v[248:251], v254 offset:49152
	ds_read_b128 v[240:243], v254 offset:57344
	v_cvt_pk_bf16_f32 v125, v128, v129
	v_cvt_pk_bf16_f32 v126, v178, v179
	v_cvt_pk_bf16_f32 v127, v202, v203
	v_cvt_pk_bf16_f32 v128, v228, v229
	v_cvt_pk_bf16_f32 v129, v230, v231
	s_waitcnt lgkmcnt(3)
	v_mfma_f32_32x32x16_bf16 v[48:63], v[114:117], v[82:85], v[48:63]
	v_add_f32_e32 v178, v176, v177
	v_add_f32_e32 v179, v177, v176
	v_mov_b32_e32 v228, v178
	s_nop 1
	v_permlane32_swap_b32_e32 v178, v228
	v_permlane32_swap_b32_e32 v122, v124
	s_waitcnt lgkmcnt(2)
	v_mfma_f32_32x32x16_bf16 v[32:47], v[118:121], v[82:85], v[32:47]
	v_add_u32_e32 v246, s63, v185
	ds_read_b64_tr_b16 v[114:115], v246 offset:0
	ds_read_b64_tr_b16 v[116:117], v246 offset:2048
	ds_read_b64_tr_b16 v[118:119], v246 offset:4096
	ds_read_b64_tr_b16 v[120:121], v246 offset:6144
	v_permlane32_swap_b32_e32 v123, v125
	v_permlane32_swap_b32_e32 v126, v128
	v_permlane32_swap_b32_e32 v127, v129
	s_waitcnt lgkmcnt(5)
	v_mfma_f32_32x32x16_bf16 v[48:63], v[248:251], v[86:89], v[48:63]
	s_waitcnt lgkmcnt(4)
	v_mfma_f32_32x32x16_bf16 v[32:47], v[240:243], v[86:89], v[32:47]
	ds_read_b64_tr_b16 v[248:249], v246 offset:8192
	ds_read_b64_tr_b16 v[250:251], v246 offset:10240
	ds_read_b64_tr_b16 v[240:241], v246 offset:12288
	ds_read_b64_tr_b16 v[242:243], v246 offset:14336
	s_waitcnt lgkmcnt(8)
	s_cmp_eq_u64 s[2:3], 0
	s_cbranch_scc0 .Lattn_cb3
	s_barrier
; #define SWRITE(b, i) do { if (isK) { *(bf16x8*)(K_lds + (b) * SHM_K + kst0) = sr_[i].a0; *(bf16x8*)(K_lds + (b) * SHM_K + kst1) = sr_[i].a1; } \
;     else { *(bf16x8*)(V_lds + (b) * SHM_V + vst0) = sr_[i].a0; *(bf16x8*)(V_lds + (b) * SHM_V + vst1) = sr_[i].a1; } \
;     if (rwr) *(bf16x8*)(K_lds + (b) * SHM_K + rst) = sr_[i].rr; } while (0)
; #define SWAIT() asm volatile("s_waitcnt vmcnt(3)" ::: "memory")
; __device__ __forceinline__ void partialSM(f32x16& p0, f32x16& p1, float& m_reg, float& mn, float& alpha) {
;     constexpr float Cc = SCALE * 1.4426950408889634f;
;     float pmax = p0[0];
; #pragma unroll
;     for (int r = 1; r < 16; ++r) pmax = fmaxf(pmax, p0[r]);
; #pragma unroll
;     for (int r = 0; r < 16; ++r) pmax = fmaxf(pmax, p1[r]);
;     { auto rr = __builtin_amdgcn_permlane32_swap(__float_as_uint(pmax), __float_as_uint(pmax), false, false);
;       pmax = fmaxf(__uint_as_float(rr[0]), __uint_as_float(rr[1])); }
;     if (__builtin_expect(__all(pmax - m_reg <= THR / SCALE), 1)) { mn = m_reg; alpha = 1.f; }
;     else { mn = fmaxf(m_reg, pmax); alpha = __builtin_amdgcn_exp2f((m_reg - mn) * Cc); m_reg = mn; }
;     const float mnC = -mn * Cc;
;     { typedef float f32x2 __attribute__((ext_vector_type(2))); const f32x2 c2 = {Cc, Cc}, m2 = {mnC, mnC};
; #pragma unroll
;       for (int r = 0; r < 16; r += 2) { f32x2 t = {p0[r], p0[r + 1]}; t = __builtin_elementwise_fma(t, c2, m2); p0[r] = t.x; p0[r + 1] = t.y; }
; #pragma unroll
;       for (int r = 0; r < 16; r += 2) { f32x2 t = {p1[r], p1[r + 1]}; t = __builtin_elementwise_fma(t, c2, m2); p1[r] = t.x; p1[r + 1] = t.y; } }
; #pragma unroll
;     for (int r = 0; r < 16; ++r) p0[r] = __builtin_amdgcn_exp2f(p0[r]);
; }
; __device__ __forceinline__ void attn_body(const bf16_t* __restrict__ Qb, const bf16_t* __restrict__ KVh, const bf16_t* __restrict__ KR, const float* __restrict__ ropeq,
;                                           bf16_t* __restrict__ Ob, int seq, char* lds, const int tid) {
;     ...
;         pv_d0(o, vb0 + bp * (int)SHM_V, pa0, pa1, pa2, pa3); partialSM(pA0, pA1, m_reg, mnA, alA);
;         SWAIT(); SWRITE(bn, SO);
;         RESC(alA); __syncthreads();
;         { const int t = bp; bp = bc; bc = bn; bn = t; }
;     }
.Lattn_cb3:
	s_waitcnt lgkmcnt(6)
	v_mfma_f32_32x32x16_bf16 v[0:15], v[232:235], v[114:117], v[0:15]
	ds_read_b64_tr_b16 v[114:115], v246 offset:512
	ds_read_b64_tr_b16 v[116:117], v246 offset:2560
	v_max_f32_e32 v244, v48, v49
	v_max_f32_e32 v245, v32, v33
	v_max3_f32 v244, v244, v50, v51
	v_max3_f32 v245, v245, v34, v35
	v_max3_f32 v244, v244, v52, v53
	v_max3_f32 v245, v245, v36, v37
	v_add_f32_e32 v247, v174, v175
	v_fmac_f32_e32 v247, v225, v163
	v_add_f32_e32 v163, v178, v228
	v_fmac_f32_e32 v163, v247, v227
	s_waitcnt lgkmcnt(6)
	v_mfma_f32_32x32x16_bf16 v[0:15], v[236:239], v[118:121], v[0:15]
	ds_read_b64_tr_b16 v[118:119], v246 offset:4608
	ds_read_b64_tr_b16 v[120:121], v246 offset:6656
	v_max3_f32 v244, v244, v54, v55
	v_max3_f32 v245, v245, v38, v39
	v_max3_f32 v244, v244, v56, v57
	v_max3_f32 v245, v245, v40, v41
	v_max3_f32 v244, v244, v58, v59
	v_max3_f32 v245, v245, v42, v43
	v_max3_f32 v244, v244, v60, v61
	s_waitcnt lgkmcnt(6)
	v_mfma_f32_32x32x16_bf16 v[0:15], v[122:125], v[248:251], v[0:15]
	ds_read_b64_tr_b16 v[248:249], v246 offset:8704
	ds_read_b64_tr_b16 v[250:251], v246 offset:10752
	v_max3_f32 v245, v245, v44, v45
	v_max3_f32 v244, v244, v62, v63
	v_max3_f32 v245, v245, v46, v47
	v_max_f32_e32 v244, v244, v245
	v_mov_b32_e32 v245, v244
	s_nop 1
	v_permlane32_swap_b32_e32 v244, v245
	v_max_f32_e32 v244, v244, v245
	v_sub_f32_e32 v247, v244, v180
	s_waitcnt lgkmcnt(6)
	v_mfma_f32_32x32x16_bf16 v[0:15], v[126:129], v[240:243], v[0:15]
	ds_read_b64_tr_b16 v[240:241], v246 offset:12800
	ds_read_b64_tr_b16 v[242:243], v246 offset:14848
	v_cmp_ge_f32_e32 vcc, s67, v247
	v_max_f32_e32 v244, v180, v244
	v_sub_f32_e32 v247, v180, v244
	v_mul_f32_e32 v247, 0x3e16c740, v247
	v_exp_f32_e32 v226, v247
	s_cmp_eq_u64 vcc, exec
	s_cselect_b64 s[44:45], -1, 0
	v_cndmask_b32_e64 v179, v244, v180, s[44:45]
	s_waitcnt lgkmcnt(6)
	v_mfma_f32_32x32x16_bf16 v[16:31], v[232:235], v[114:117], v[16:31]
	v_mul_f32_e32 v254, 0xbe16c740, v179
	v_cndmask_b32_e64 v226, v226, 1.0, s[44:45]
	v_fma_f32 v48, v48, s52, v254
	v_fma_f32 v49, v49, s52, v254
	v_fma_f32 v50, v50, s52, v254
	v_fma_f32 v51, v51, s52, v254
	v_fma_f32 v52, v52, s52, v254
	v_fma_f32 v53, v53, s52, v254
	v_fma_f32 v54, v54, s52, v254
	v_fma_f32 v55, v55, s52, v254
	v_fma_f32 v56, v56, s52, v254
	v_fma_f32 v57, v57, s52, v254
	v_fma_f32 v58, v58, s52, v254
	v_fma_f32 v59, v59, s52, v254
	v_exp_f32_e32 v116, v48
	v_exp_f32_e32 v117, v49
	v_exp_f32_e32 v114, v50
	v_exp_f32_e32 v115, v51
	s_waitcnt lgkmcnt(4)
	v_mfma_f32_32x32x16_bf16 v[16:31], v[236:239], v[118:121], v[16:31]
	v_fma_f32 v60, v60, s52, v254
	v_fma_f32 v61, v61, s52, v254
	v_fma_f32 v62, v62, s52, v254
	v_fma_f32 v63, v63, s52, v254
	v_fma_f32 v180, v32, s52, v254
	v_fma_f32 v181, v33, s52, v254
	v_fma_f32 v176, v34, s52, v254
	v_fma_f32 v177, v35, s52, v254
	v_exp_f32_e32 v112, v52
	v_exp_f32_e32 v113, v53
	v_exp_f32_e32 v110, v54
	v_exp_f32_e32 v111, v55
	v_fma_f32 v120, v44, s52, v254
	v_fma_f32 v121, v45, s52, v254
	v_fma_f32 v118, v46, s52, v254
	v_fma_f32 v119, v47, s52, v254
	s_waitcnt lgkmcnt(2)
	v_mfma_f32_32x32x16_bf16 v[16:31], v[122:125], v[248:251], v[16:31]
	v_exp_f32_e32 v108, v56
	v_exp_f32_e32 v109, v57
	v_exp_f32_e32 v106, v58
	v_exp_f32_e32 v107, v59
	v_exp_f32_e32 v102, v60
	v_exp_f32_e32 v103, v61
	v_exp_f32_e32 v104, v62
	v_exp_f32_e32 v105, v63
	v_fma_f32 v124, v40, s52, v254
	v_fma_f32 v125, v41, s52, v254
	v_fma_f32 v122, v42, s52, v254
	v_fma_f32 v123, v43, s52, v254
	s_waitcnt lgkmcnt(0)
	v_mfma_f32_32x32x16_bf16 v[16:31], v[126:129], v[240:243], v[16:31]
	v_fma_f32 v128, v36, s52, v254
	v_fma_f32 v129, v37, s52, v254
	v_fma_f32 v126, v38, s52, v254
	v_fma_f32 v127, v39, s52, v254
	v_cmp_gt_f32_e32 vcc, 1.0, v226
	s_cbranch_vccz .Lattn_rsA
	s_nop 7
	s_nop 5
	s_and_saveexec_b64 s[46:47], s[4:5]
	ds_write_b32 v216, v226 offset:128
	s_or_b64 exec, exec, s[46:47]
	s_waitcnt lgkmcnt(0)
	v_add_u32_e32 v232, v139, v187
	ds_read_b128 v[236:239], v232 offset:192
	ds_read_b128 v[240:243], v232 offset:160
	ds_read_b128 v[248:251], v232 offset:128
	ds_read_b128 v[232:235], v232 offset:224
	s_waitcnt lgkmcnt(0)
	v_mul_f32_e32 v12, v12, v232
	v_mul_f32_e32 v13, v13, v233
	v_mul_f32_e32 v14, v14, v234
	v_mul_f32_e32 v15, v15, v235
	v_mul_f32_e32 v8, v8, v236
	v_mul_f32_e32 v9, v9, v237
	v_mul_f32_e32 v10, v10, v238
	v_mul_f32_e32 v11, v11, v239
	v_mul_f32_e32 v4, v4, v240
	v_mul_f32_e32 v5, v5, v241
	v_mul_f32_e32 v6, v6, v242
	v_mul_f32_e32 v7, v7, v243
	v_mul_f32_e32 v0, v0, v248
	v_mul_f32_e32 v1, v1, v249
	v_mul_f32_e32 v2, v2, v250
	v_mul_f32_e32 v3, v3, v251
	v_mul_f32_e32 v28, v28, v232
	v_mul_f32_e32 v29, v29, v233
	v_mul_f32_e32 v30, v30, v234
	v_mul_f32_e32 v31, v31, v235
	v_mul_f32_e32 v24, v24, v236
	v_mul_f32_e32 v25, v25, v237
	v_mul_f32_e32 v26, v26, v238
	v_mul_f32_e32 v27, v27, v239
	v_mul_f32_e32 v20, v20, v240
	v_mul_f32_e32 v21, v21, v241
	v_mul_f32_e32 v22, v22, v242
	v_mul_f32_e32 v23, v23, v243
	v_mul_f32_e32 v16, v16, v248
	v_mul_f32_e32 v17, v17, v249
	v_mul_f32_e32 v18, v18, v250
	v_mul_f32_e32 v19, v19, v251
.Lattn_rsA:
	s_waitcnt lgkmcnt(0)
	s_cmp_gt_u32 s17, 60
	s_cselect_b64 s[12:13], -1, 0
	s_add_i32 s17, s17, 2
	v_lshl_add_u64 v[168:169], v[168:169], 0, s[56:57]
	v_lshl_add_u64 v[170:171], v[170:171], 0, s[24:25]
	v_lshl_add_u64 v[172:173], v[172:173], 0, s[24:25]
	s_cmp_eq_u64 s[2:3], 0
	s_cbranch_scc1 .Lattn_cb4
	s_barrier
.Lattn_cb4:
	s_and_b64 vcc, exec, s[12:13]
	s_cbranch_vccnz .LBB0_72
	s_mov_b32 s6, s18
	s_mov_b32 s18, s16
	s_mov_b32 s16, s19
	s_mov_b32 s23, s59
	s_mov_b32 s59, s58
	s_mov_b32 s58, s60
	s_mov_b32 s60, s23
	v_mov_b32_e32 v225, v226
	s_branch .Lattn_loop

; __device__ __forceinline__ void partialSM(f32x16& p0, f32x16& p1, float& m_reg, float& mn, float& alpha) {
;     constexpr float Cc = SCALE * 1.4426950408889634f;
;     float pmax = p0[0];
; #pragma unroll
;     for (int r = 1; r < 16; ++r) pmax = fmaxf(pmax, p0[r]);
; #pragma unroll
;     for (int r = 0; r < 16; ++r) pmax = fmaxf(pmax, p1[r]);
;     { auto rr = __builtin_amdgcn_permlane32_swap(__float_as_uint(pmax), __float_as_uint(pmax), false, false);
;       pmax = fmaxf(__uint_as_float(rr[0]), __uint_as_float(rr[1])); }
;     if (__builtin_expect(__all(pmax - m_reg <= THR / SCALE), 1)) { mn = m_reg; alpha = 1.f; }
;     else { mn = fmaxf(m_reg, pmax); alpha = __builtin_amdgcn_exp2f((m_reg - mn) * Cc); m_reg = mn; }
;     const float mnC = -mn * Cc;
;     { typedef float f32x2 __attribute__((ext_vector_type(2))); const f32x2 c2 = {Cc, Cc}, m2 = {mnC, mnC};
; #pragma unroll
;       for (int r = 0; r < 16; r += 2) { f32x2 t = {p0[r], p0[r + 1]}; t = __builtin_elementwise_fma(t, c2, m2); p0[r] = t.x; p0[r + 1] = t.y; }
; #pragma unroll
;       for (int r = 0; r < 16; r += 2) { f32x2 t = {p1[r], p1[r + 1]}; t = __builtin_elementwise_fma(t, c2, m2); p1[r] = t.x; p1[r + 1] = t.y; } }
; #pragma unroll
;     for (int r = 0; r < 16; ++r) p0[r] = __builtin_amdgcn_exp2f(p0[r]);
; }
; __device__ __forceinline__ void finishSM(f32x16& p0, f32x16& p1, float alpha, float& l_reg, bf16x8& pa0, bf16x8& pa1, bf16x8& pa2, bf16x8& pa3) {
; #pragma unroll
;     for (int r = 0; r < 16; ++r) p1[r] = __builtin_amdgcn_exp2f(p1[r]);
;     float ps;
;     { typedef float f32x2 __attribute__((ext_vector_type(2))); f32x2 s0 = {p0[0], p0[1]}, s1 = {p1[0], p1[1]};
; __device__ __forceinline__ void attn_body(const bf16_t* __restrict__ Qb, const bf16_t* __restrict__ KVh, const bf16_t* __restrict__ KR, const float* __restrict__ ropeq,
;                                           bf16_t* __restrict__ Ob, int seq, char* lds, const int tid) {
;     ...
;     SBAR(); qkt(pB0, pB1, K_lds + bc * SHM_K, qr, r32, hi);
;     finishSM(pA0, pA1, alA, l_reg, pa0, pa1, pa2, pa3); SBAR();
;     pv_d0(o, vb0 + bp * (int)SHM_V, pa0, pa1, pa2, pa3); partialSM(pB0, pB1, m_reg, mnB, alB);
;     RESC(alB);
;     finishSM(pB0, pB1, alB, l_reg, pa0, pa1, pa2, pa3); SBAR();
;     pv_d0(o, vb0 + bc * (int)SHM_V, pa0, pa1, pa2, pa3);
;     if (hi == 0) li_l[r32] = l_reg; asm volatile("s_waitcnt lgkmcnt(0)" ::: "memory");
.LBB0_76:
	v_cndmask_b32_e64 v69, v69, v179, s[6:7]
	v_mul_f32_e32 v70, 0xbe16c740, v69
	v_pk_fma_f32 v[48:49], v[48:49], s[52:53], v[70:71] op_sel_hi:[1,0,0]
	v_pk_fma_f32 v[50:51], v[50:51], s[52:53], v[70:71] op_sel_hi:[1,0,0]
	v_pk_fma_f32 v[32:33], v[32:33], s[52:53], v[70:71] op_sel_hi:[1,0,0]
	v_pk_fma_f32 v[34:35], v[34:35], s[52:53], v[70:71] op_sel_hi:[1,0,0]
	v_pk_fma_f32 v[52:53], v[52:53], s[52:53], v[70:71] op_sel_hi:[1,0,0]
	v_pk_fma_f32 v[54:55], v[54:55], s[52:53], v[70:71] op_sel_hi:[1,0,0]
	v_pk_fma_f32 v[56:57], v[56:57], s[52:53], v[70:71] op_sel_hi:[1,0,0]
	v_pk_fma_f32 v[58:59], v[58:59], s[52:53], v[70:71] op_sel_hi:[1,0,0]
	v_pk_fma_f32 v[60:61], v[60:61], s[52:53], v[70:71] op_sel_hi:[1,0,0]
	v_pk_fma_f32 v[62:63], v[62:63], s[52:53], v[70:71] op_sel_hi:[1,0,0]
	v_pk_fma_f32 v[36:37], v[36:37], s[52:53], v[70:71] op_sel_hi:[1,0,0]
	v_pk_fma_f32 v[38:39], v[38:39], s[52:53], v[70:71] op_sel_hi:[1,0,0]
	v_pk_fma_f32 v[40:41], v[40:41], s[52:53], v[70:71] op_sel_hi:[1,0,0]
	v_pk_fma_f32 v[42:43], v[42:43], s[52:53], v[70:71] op_sel_hi:[1,0,0]
	v_pk_fma_f32 v[44:45], v[44:45], s[52:53], v[70:71] op_sel_hi:[1,0,0]
	v_pk_fma_f32 v[46:47], v[46:47], s[52:53], v[70:71] op_sel_hi:[1,0,0]
	v_exp_f32_e32 v48, v48
	v_exp_f32_e32 v49, v49
	v_exp_f32_e32 v50, v50
	v_exp_f32_e32 v51, v51
	v_exp_f32_e32 v70, v32
	v_exp_f32_e32 v71, v33
	v_exp_f32_e32 v72, v34
	v_exp_f32_e32 v73, v35
	v_exp_f32_e32 v52, v52
	v_exp_f32_e32 v53, v53
	v_exp_f32_e32 v74, v36
	v_exp_f32_e32 v75, v37
	v_exp_f32_e32 v54, v54
	v_exp_f32_e32 v55, v55
	v_exp_f32_e32 v76, v38
	v_exp_f32_e32 v77, v39
	v_exp_f32_e32 v56, v56
	v_exp_f32_e32 v57, v57
	v_exp_f32_e32 v78, v40
	v_exp_f32_e32 v79, v41
	v_exp_f32_e32 v58, v58
	v_exp_f32_e32 v59, v59
	v_exp_f32_e32 v80, v42
	v_exp_f32_e32 v81, v43
	v_pk_add_f32 v[32:33], v[48:49], v[50:51]
	v_pk_add_f32 v[34:35], v[70:71], v[72:73]
	v_exp_f32_e32 v60, v60
	v_exp_f32_e32 v61, v61
	v_exp_f32_e32 v82, v44
	v_exp_f32_e32 v83, v45
	v_pk_add_f32 v[32:33], v[52:53], v[32:33]
	v_pk_add_f32 v[34:35], v[74:75], v[34:35]
	v_exp_f32_e32 v62, v62
	v_exp_f32_e32 v63, v63
	v_exp_f32_e32 v84, v46
	v_exp_f32_e32 v85, v47
	v_pk_add_f32 v[32:33], v[54:55], v[32:33]
	v_pk_add_f32 v[34:35], v[76:77], v[34:35]
	v_pk_add_f32 v[32:33], v[56:57], v[32:33]
	v_pk_add_f32 v[34:35], v[78:79], v[34:35]
	v_pk_add_f32 v[32:33], v[58:59], v[32:33]
	v_pk_add_f32 v[34:35], v[80:81], v[34:35]
	v_pk_add_f32 v[32:33], v[60:61], v[32:33]
	v_pk_add_f32 v[34:35], v[82:83], v[34:35]
	v_pk_add_f32 v[32:33], v[62:63], v[32:33]
	v_pk_add_f32 v[34:35], v[84:85], v[34:35]
	s_nop 0
	v_pk_add_f32 v[32:33], v[34:35], v[32:33]
	v_cvt_pk_bf16_f32 v34, v48, v49
	v_cvt_pk_bf16_f32 v35, v50, v51
	v_cvt_pk_bf16_f32 v36, v52, v53
	v_cvt_pk_bf16_f32 v37, v54, v55
	v_cvt_pk_bf16_f32 v38, v56, v57
	s_nop 0
	v_pk_add_f32 v[32:33], v[32:33], v[32:33] op_sel:[0,1] op_sel_hi:[1,0]
	v_cvt_pk_bf16_f32 v39, v58, v59
	v_cvt_pk_bf16_f32 v40, v60, v61
	v_cvt_pk_bf16_f32 v41, v62, v63
	v_cvt_pk_bf16_f32 v42, v70, v71
	v_cvt_pk_bf16_f32 v43, v72, v73
	s_nop 0
	v_mov_b32_e32 v33, v32
	s_nop 1
	v_permlane32_swap_b32_e32 v32, v33
	v_cvt_pk_bf16_f32 v44, v74, v75
	v_cvt_pk_bf16_f32 v45, v76, v77
	v_cvt_pk_bf16_f32 v46, v78, v79
	v_cvt_pk_bf16_f32 v47, v80, v81
	v_cvt_pk_bf16_f32 v48, v82, v83
	v_cvt_pk_bf16_f32 v49, v84, v85
	v_permlane32_swap_b32_e32 v34, v36
	v_permlane32_swap_b32_e32 v35, v37
	v_permlane32_swap_b32_e32 v38, v40
	v_permlane32_swap_b32_e32 v39, v41
	v_permlane32_swap_b32_e32 v42, v44
	v_permlane32_swap_b32_e32 v43, v45
	v_permlane32_swap_b32_e32 v46, v48
	v_permlane32_swap_b32_e32 v47, v49
	ds_read_b64_tr_b16 v[50:51], v185 offset:1024
	ds_read_b64_tr_b16 v[52:53], v185 offset:3072
	ds_read_b64_tr_b16 v[54:55], v185 offset:5120
	ds_read_b64_tr_b16 v[56:57], v185 offset:7168
	ds_read_b64_tr_b16 v[58:59], v185 offset:9216
	ds_read_b64_tr_b16 v[60:61], v185 offset:11264
	ds_read_b64_tr_b16 v[70:71], v185 offset:13312
	ds_read_b64_tr_b16 v[72:73], v185 offset:15360
	s_waitcnt lgkmcnt(0)
	s_nop 0
	v_mfma_f32_32x32x16_bf16 v[0:15], v[34:37], v[50:53], v[0:15]
	ds_read_b64_tr_b16 v[50:51], v185 offset:1536
	ds_read_b64_tr_b16 v[52:53], v185 offset:3584
	v_mfma_f32_32x32x16_bf16 v[0:15], v[38:41], v[54:57], v[0:15]
	ds_read_b64_tr_b16 v[54:55], v185 offset:5632
	ds_read_b64_tr_b16 v[56:57], v185 offset:7680
	v_mfma_f32_32x32x16_bf16 v[0:15], v[42:45], v[58:61], v[0:15]
	ds_read_b64_tr_b16 v[58:59], v185 offset:9728
	ds_read_b64_tr_b16 v[60:61], v185 offset:11776
	v_mfma_f32_32x32x16_bf16 v[0:15], v[46:49], v[70:73], v[0:15]
	ds_read_b64_tr_b16 v[70:71], v185 offset:13824
	ds_read_b64_tr_b16 v[72:73], v185 offset:15872
	s_waitcnt lgkmcnt(0)
	v_mfma_f32_32x32x16_bf16 v[16:31], v[34:37], v[50:53], v[16:31]
	v_mfma_f32_32x32x16_bf16 v[16:31], v[38:41], v[54:57], v[16:31]
	v_mfma_f32_32x32x16_bf16 v[16:31], v[42:45], v[58:61], v[16:31]
	v_mfma_f32_32x32x16_bf16 v[16:31], v[46:49], v[70:73], v[16:31]
	s_and_saveexec_b64 s[6:7], s[4:5]
	s_cbranch_execz .LBB0_42
	v_add_f32_e32 v34, v66, v67
	v_fmac_f32_e32 v34, v163, v226
	v_add_f32_e32 v32, v32, v33
	v_fmac_f32_e32 v32, v34, v68
	ds_write_b32 v216, v32
	s_branch .LBB0_42
